# union + static s_setprio 1 for leading attention waves
# speedup vs baseline: 1.0070x; 1.0070x over previous
.LBB0_722:
	v_max3_f32 v0, v142, s63, v143
	v_max3_f32 v0, v0, v144, v145
	v_max3_f32 v0, v0, v138, v139
	v_max3_f32 v0, v0, v140, v141
	v_max3_f32 v0, v0, v118, v119
	v_max3_f32 v0, v0, v120, v121
	v_max3_f32 v0, v0, v114, v115
	v_max3_f32 v0, v0, v116, v117
	ds_bpermute_b32 v190, v232, v0
	s_andn2_b64 vcc, exec, s[6:7]
	s_waitcnt lgkmcnt(0)
	v_max_f32_e32 v190, v190, v190
	v_max_f32_e32 v0, v0, v190
	ds_bpermute_b32 v190, v233, v0
	s_waitcnt lgkmcnt(0)
	v_max3_f32 v239, v189, v0, v190
	v_sub_f32_e32 v138, v138, v239
	v_exp_f32_e32 v203, v138
	v_sub_f32_e32 v138, v139, v239
	v_exp_f32_e32 v201, v138
	v_sub_f32_e32 v138, v140, v239
	v_sub_f32_e32 v114, v114, v239
	v_exp_f32_e32 v199, v138
	v_sub_f32_e32 v138, v141, v239
	v_exp_f32_e32 v141, v114
	v_sub_f32_e32 v114, v115, v239
	v_exp_f32_e32 v139, v114
	v_sub_f32_e32 v114, v116, v239
	v_sub_f32_e32 v0, v189, v239
	v_sub_f32_e32 v143, v143, v239
	v_exp_f32_e32 v189, v114
	v_sub_f32_e32 v114, v117, v239
	v_exp_f32_e32 v209, v143
	v_exp_f32_e32 v143, v114
	v_max3_f32 v114, v134, s63, v135
	v_max3_f32 v114, v114, v136, v137
	v_max3_f32 v114, v114, v130, v131
	v_sub_f32_e32 v118, v118, v239
	v_max3_f32 v114, v114, v132, v133
	v_exp_f32_e32 v195, v118
	v_sub_f32_e32 v118, v119, v239
	v_max3_f32 v114, v114, v126, v127
	v_exp_f32_e32 v193, v118
	v_sub_f32_e32 v118, v120, v239
	v_max3_f32 v114, v114, v128, v129
	v_sub_f32_e32 v145, v145, v239
	v_exp_f32_e32 v191, v118
	v_sub_f32_e32 v118, v121, v239
	v_max3_f32 v114, v114, v122, v123
	v_exp_f32_e32 v205, v145
	v_exp_f32_e32 v145, v118
	v_max3_f32 v118, v114, v124, v125
	ds_bpermute_b32 v119, v232, v118
	v_exp_f32_e32 v197, v138
	v_sub_f32_e32 v142, v142, v239
	v_exp_f32_e32 v211, v142
	v_sub_f32_e32 v144, v144, v239
	s_waitcnt lgkmcnt(0)
	v_max_f32_e32 v119, v119, v119
	v_max_f32_e32 v138, v118, v119
	ds_bpermute_b32 v140, v233, v138
	v_exp_f32_e32 v0, v0
	v_exp_f32_e32 v207, v144
	v_cvt_pk_bf16_f32 v114, v211, v209
	v_cvt_pk_bf16_f32 v115, v207, v205
	s_waitcnt lgkmcnt(0)
	v_max3_f32 v240, v188, v138, v140
	v_sub_f32_e32 v130, v130, v240
	v_sub_f32_e32 v134, v134, v240
	v_exp_f32_e32 v202, v130
	v_sub_f32_e32 v130, v131, v240
	v_sub_f32_e32 v126, v126, v240
	v_sub_f32_e32 v122, v122, v240
	v_exp_f32_e32 v210, v134
	v_sub_f32_e32 v134, v135, v240
	v_exp_f32_e32 v200, v130
	v_sub_f32_e32 v130, v132, v240
	v_exp_f32_e32 v194, v126
	v_sub_f32_e32 v126, v127, v240
	v_exp_f32_e32 v140, v122
	v_sub_f32_e32 v122, v123, v240
	v_sub_f32_e32 v142, v188, v240
	v_exp_f32_e32 v208, v134
	v_sub_f32_e32 v134, v136, v240
	v_exp_f32_e32 v198, v130
	v_sub_f32_e32 v130, v133, v240
	v_exp_f32_e32 v192, v126
	v_sub_f32_e32 v126, v128, v240
	v_exp_f32_e32 v138, v122
	v_sub_f32_e32 v122, v124, v240
	v_exp_f32_e32 v206, v134
	v_sub_f32_e32 v134, v137, v240
	v_exp_f32_e32 v196, v130
	v_exp_f32_e32 v190, v126
	v_sub_f32_e32 v126, v129, v240
	v_exp_f32_e32 v130, v142
	v_exp_f32_e32 v188, v122
	v_sub_f32_e32 v122, v125, v240
	v_exp_f32_e32 v204, v134
	v_exp_f32_e32 v144, v126
	v_exp_f32_e32 v142, v122
	v_pk_mul_f32 v[112:113], v[112:113], v[0:1] op_sel_hi:[1,0]
	v_pk_mul_f32 v[110:111], v[110:111], v[0:1] op_sel_hi:[1,0]
	v_pk_mul_f32 v[108:109], v[108:109], v[0:1] op_sel_hi:[1,0]
	v_pk_mul_f32 v[106:107], v[106:107], v[0:1] op_sel_hi:[1,0]
	v_pk_mul_f32 v[104:105], v[104:105], v[0:1] op_sel_hi:[1,0]
	v_pk_mul_f32 v[102:103], v[102:103], v[0:1] op_sel_hi:[1,0]
	v_pk_mul_f32 v[100:101], v[100:101], v[0:1] op_sel_hi:[1,0]
	v_pk_mul_f32 v[98:99], v[98:99], v[0:1] op_sel_hi:[1,0]
	v_pk_mul_f32 v[92:93], v[92:93], v[0:1] op_sel_hi:[1,0]
	v_pk_mul_f32 v[90:91], v[90:91], v[0:1] op_sel_hi:[1,0]
	v_pk_mul_f32 v[72:73], v[72:73], v[0:1] op_sel_hi:[1,0]
	v_pk_mul_f32 v[70:71], v[70:71], v[0:1] op_sel_hi:[1,0]
	v_pk_mul_f32 v[40:41], v[40:41], v[0:1] op_sel_hi:[1,0]
	v_pk_mul_f32 v[38:39], v[38:39], v[0:1] op_sel_hi:[1,0]
	v_pk_mul_f32 v[36:37], v[36:37], v[0:1] op_sel_hi:[1,0]
	v_pk_mul_f32 v[34:35], v[34:35], v[0:1] op_sel_hi:[1,0]
	v_pk_mul_f32 v[32:33], v[32:33], v[130:131] op_sel_hi:[1,0]
	v_pk_mul_f32 v[30:31], v[30:31], v[130:131] op_sel_hi:[1,0]
	v_pk_mul_f32 v[28:29], v[28:29], v[130:131] op_sel_hi:[1,0]
	v_pk_mul_f32 v[26:27], v[26:27], v[130:131] op_sel_hi:[1,0]
	v_pk_mul_f32 v[24:25], v[24:25], v[130:131] op_sel_hi:[1,0]
	v_pk_mul_f32 v[22:23], v[22:23], v[130:131] op_sel_hi:[1,0]
	v_pk_mul_f32 v[20:21], v[20:21], v[130:131] op_sel_hi:[1,0]
	v_pk_mul_f32 v[18:19], v[18:19], v[130:131] op_sel_hi:[1,0]
	v_pk_mul_f32 v[16:17], v[16:17], v[130:131] op_sel_hi:[1,0]
	v_pk_mul_f32 v[14:15], v[14:15], v[130:131] op_sel_hi:[1,0]
	v_pk_mul_f32 v[12:13], v[12:13], v[130:131] op_sel_hi:[1,0]
	v_pk_mul_f32 v[10:11], v[10:11], v[130:131] op_sel_hi:[1,0]
	v_pk_mul_f32 v[8:9], v[8:9], v[130:131] op_sel_hi:[1,0]
	v_pk_mul_f32 v[6:7], v[6:7], v[130:131] op_sel_hi:[1,0]
	v_pk_mul_f32 v[4:5], v[4:5], v[130:131] op_sel_hi:[1,0]
	v_pk_mul_f32 v[2:3], v[2:3], v[130:131] op_sel_hi:[1,0]
	v_cvt_pk_bf16_f32 v116, v203, v201
	v_cvt_pk_bf16_f32 v117, v199, v197
	v_cvt_pk_bf16_f32 v118, v195, v193
	v_cvt_pk_bf16_f32 v119, v191, v145
	v_cvt_pk_bf16_f32 v120, v141, v139
	v_cvt_pk_bf16_f32 v121, v189, v143
	v_cvt_pk_bf16_f32 v122, v210, v208
	v_cvt_pk_bf16_f32 v123, v206, v204
	v_cvt_pk_bf16_f32 v124, v202, v200
	v_cvt_pk_bf16_f32 v125, v198, v196
	v_cvt_pk_bf16_f32 v126, v194, v192
	v_cvt_pk_bf16_f32 v127, v190, v144
	v_cvt_pk_bf16_f32 v128, v140, v138
	v_cvt_pk_bf16_f32 v129, v188, v142
	s_cbranch_vccnz .LBB0_727
	s_setprio 1
	v_add_u32_e32 v131, s54, v160
	ds_read_b128 v[132:135], v131 offset:49152
	ds_read_b128 v[220:223], v131 offset:50176
	ds_read_b128 v[242:245], v131 offset:51200
	ds_read_b128 v[246:249], v131 offset:52224
	s_waitcnt lgkmcnt(3)
	v_mfma_f32_16x16x32_bf16 v[110:113], v[132:135], v[114:117], v[110:113]
	v_mfma_f32_16x16x32_bf16 v[30:33], v[132:135], v[122:125], v[30:33]
	s_waitcnt lgkmcnt(2)
	v_mfma_f32_16x16x32_bf16 v[110:113], v[220:223], v[118:121], v[110:113]
	v_mfma_f32_16x16x32_bf16 v[30:33], v[220:223], v[126:129], v[30:33]
	ds_read_b128 v[132:135], v131 offset:53248
	ds_read_b128 v[220:223], v131 offset:54272
	s_waitcnt lgkmcnt(2)
	v_mfma_f32_16x16x32_bf16 v[106:109], v[242:245], v[114:117], v[106:109]
	v_mfma_f32_16x16x32_bf16 v[26:29], v[242:245], v[122:125], v[26:29]
	v_mfma_f32_16x16x32_bf16 v[106:109], v[246:249], v[118:121], v[106:109]
	v_mfma_f32_16x16x32_bf16 v[26:29], v[246:249], v[126:129], v[26:29]
	ds_read_b128 v[242:245], v131 offset:55296
	ds_read_b128 v[246:249], v131 offset:56320
	s_waitcnt lgkmcnt(2)
	v_mfma_f32_16x16x32_bf16 v[102:105], v[132:135], v[114:117], v[102:105]
	v_mfma_f32_16x16x32_bf16 v[22:25], v[132:135], v[122:125], v[22:25]
	v_mfma_f32_16x16x32_bf16 v[102:105], v[220:223], v[118:121], v[102:105]
	v_mfma_f32_16x16x32_bf16 v[22:25], v[220:223], v[126:129], v[22:25]
	ds_read_b128 v[132:135], v131 offset:57344
	ds_read_b128 v[220:223], v131 offset:58368
	s_waitcnt lgkmcnt(2)
	v_mfma_f32_16x16x32_bf16 v[98:101], v[242:245], v[114:117], v[98:101]
	v_mfma_f32_16x16x32_bf16 v[18:21], v[242:245], v[122:125], v[18:21]
	v_mfma_f32_16x16x32_bf16 v[98:101], v[246:249], v[118:121], v[98:101]
	v_mfma_f32_16x16x32_bf16 v[18:21], v[246:249], v[126:129], v[18:21]
	ds_read_b128 v[242:245], v131 offset:59392
	ds_read_b128 v[246:249], v131 offset:60416
	s_waitcnt lgkmcnt(2)
	v_mfma_f32_16x16x32_bf16 v[90:93], v[132:135], v[114:117], v[90:93]
	v_mfma_f32_16x16x32_bf16 v[14:17], v[132:135], v[122:125], v[14:17]
	v_mfma_f32_16x16x32_bf16 v[90:93], v[220:223], v[118:121], v[90:93]
	v_mfma_f32_16x16x32_bf16 v[14:17], v[220:223], v[126:129], v[14:17]
	ds_read_b128 v[132:135], v131 offset:61440
	ds_read_b128 v[220:223], v131 offset:62464
	s_waitcnt lgkmcnt(2)
	v_mfma_f32_16x16x32_bf16 v[70:73], v[242:245], v[114:117], v[70:73]
	v_mfma_f32_16x16x32_bf16 v[10:13], v[242:245], v[122:125], v[10:13]
	v_mfma_f32_16x16x32_bf16 v[70:73], v[246:249], v[118:121], v[70:73]
	v_mfma_f32_16x16x32_bf16 v[10:13], v[246:249], v[126:129], v[10:13]
	ds_read_b128 v[242:245], v131 offset:63488
	ds_read_b128 v[246:249], v131 offset:64512
	s_waitcnt lgkmcnt(2)
	v_mfma_f32_16x16x32_bf16 v[38:41], v[132:135], v[114:117], v[38:41]
	v_mfma_f32_16x16x32_bf16 v[6:9], v[132:135], v[122:125], v[6:9]
	v_mfma_f32_16x16x32_bf16 v[38:41], v[220:223], v[118:121], v[38:41]
	v_mfma_f32_16x16x32_bf16 v[6:9], v[220:223], v[126:129], v[6:9]
	s_waitcnt lgkmcnt(0)
	v_mfma_f32_16x16x32_bf16 v[34:37], v[242:245], v[114:117], v[34:37]
	v_mfma_f32_16x16x32_bf16 v[2:5], v[242:245], v[122:125], v[2:5]
	v_mfma_f32_16x16x32_bf16 v[34:37], v[246:249], v[118:121], v[34:37]
	v_mfma_f32_16x16x32_bf16 v[2:5], v[246:249], v[126:129], v[2:5]
	s_mov_b64 s[4:5], 0
	s_branch .LBB0_728
